# phase 5 conv rows all handled by the HGRN quarter of the grid (bx>=192), others skip them
# baseline (speedup 1.0000x reference)
; __global__ void __launch_bounds__(NT, 2) hymba_fwd(Args args) {
;     ...
;     if (IN(5)) _Pragma("unroll") for (int rep = 0; rep < NREP(5); ++rep) {
;         if (M % (4 * NGW) == 0) { for (int r = gw; r < M; r += 4 * NGW) conv_rows<4>(args, r, NGW, lane); } else { for (int r = gw; r < M; r += NGW) conv_rows<1>(args, r, NGW, lane); }
;         for (int u = vcu; u < 256; u += G) hg_c2_unit(args, args.out, lds, u, tid);
.Lp5_conv:
	s_mov_b32 s24, s98
	s_mul_i32 s72, s3, 3
	s_lshr_b32 s72, s72, 2
	s_cmp_lt_u32 s2, s72
	s_cbranch_scc0 .Lp5_conv_mine
	s_mov_b32 s101, 0
	s_branch .LBB0_939
.Lp5_conv_mine:
	s_cmp_eq_u32 s101, 0
	s_cbranch_scc1 .Lp5_sync
	s_mov_b64 exec, 1
	s_lshl_b32 s72, s33, 8
	s_add_u32 s72, s46, s72
	s_addc_u32 s73, s47, 0
	v_mov_b32_e32 v0, 0x10000
	s_mov_b32 s99, 0

; template <int NR>
; __device__ __forceinline__ void conv_rows(const Args& a, int r0, int rstride, int lane) {
;     unsigned char* ws = a.ws; const int c0 = 8 * lane;
;     const bf16* BCp = (const bf16*)(ws + WS_BC); const bf16* CUp = (const bf16*)(ws + WS_CU);
;     v4u bq[NR], u0[NR], u1[NR], u2[NR];
; #pragma unroll
;     for (int i = 0; i < NR; ++i) { const int row = r0 + i * rstride, t = row & (SEQ - 1);
;         bq[i] = *(const v4u*)(BCp + (size_t)row * 512 + c0); u0[i] = *(const v4u*)(CUp + (size_t)row * 512 + c0);
;         u1[i] = (v4u){0, 0, 0, 0}; u2[i] = (v4u){0, 0, 0, 0};
;         if (t >= 1) u1[i] = *(const v4u*)(CUp + (size_t)(row - 1) * 512 + c0);
;         if (t >= 2) u2[i] = *(const v4u*)(CUp + (size_t)(row - 2) * 512 + c0); }
;     const float* cw = a.in[I_CONVW] + c0; const float* gn = a.in[I_CONVN] + c0;
;     const f32x4 w0a = *(const f32x4*)(cw), w0b = *(const f32x4*)(cw + 4), w1a = *(const f32x4*)(cw + 512), w1b = *(const f32x4*)(cw + 516), w2a = *(const f32x4*)(cw + 1024), w2b = *(const f32x4*)(cw + 1028);
;     const f32x4 ga = *(const f32x4*)(gn), gb = *(const f32x4*)(gn + 4);
; #pragma unroll
;     for (int i = 0; i < NR; ++i) { const int row = r0 + i * rstride; float y[8]; float s = 0.f;
; #pragma unroll
;         for (int j = 0; j < 8; ++j) { const int sh = (j & 1) * 16; const unsigned ub = bq[i][j >> 1], x0 = u0[i][j >> 1], x1 = u1[i][j >> 1], x2 = u2[i][j >> 1];
;             const float B = __uint_as_float(((ub >> sh) & 0xffffu) << 16), c_0 = __uint_as_float(((x0 >> sh) & 0xffffu) << 16), c_1 = __uint_as_float(((x1 >> sh) & 0xffffu) << 16), c_2 = __uint_as_float(((x2 >> sh) & 0xffffu) << 16);
;             const float k0 = j < 4 ? w0a[j & 3] : w0b[j & 3], k1 = j < 4 ? w1a[j & 3] : w1b[j & 3], k2 = j < 4 ? w2a[j & 3] : w2b[j & 3];
;             y[j] = B * (k0 * c_2 + k1 * c_1 + k2 * c_0); s += y[j] * y[j]; }
;         s = wave_sum(s); const float rs = rsqrtf(s * (1.f / 512.f) + EPS);
; __global__ void __launch_bounds__(NT, 2) hymba_fwd(Args args) {
;     ...
;     if (IN(5)) _Pragma("unroll") for (int rep = 0; rep < NREP(5); ++rep) {
;         if (M % (4 * NGW) == 0) { for (int r = gw; r < M; r += 4 * NGW) conv_rows<4>(args, r, NGW, lane); } else { for (int r = gw; r < M; r += NGW) conv_rows<1>(args, r, NGW, lane); }
.Lp5_sync:
	s_waitcnt vmcnt(0) lgkmcnt(0)
	s_barrier
	s_mul_i32 s98, s3, 3
	s_lshr_b32 s98, s98, 2
	s_sub_i32 s24, s2, s98
	s_lshl_b32 s24, s24, 3
	s_add_i32 s24, s24, s88
	s_sub_i32 s98, s3, s98
	s_lshl_b32 s4, s98, 5
	s_lshl_b32 s98, s98, 3
	s_mov_b32 s99, 0
	s_abs_i32 s6, s4
	s_waitcnt vmcnt(0)
	v_cvt_f32_u32_e32 v0, s6
	s_sub_i32 s7, 0, s6
	s_load_dwordx4 s[16:19], s[0:1], 0xa8
	v_mov_b32_e32 v97, 0
	v_rcp_iflag_f32_e32 v0, v0
	v_lshlrev_b32_e32 v96, 4, v208
	s_mov_b64 s[4:5], 0xb000000
	v_mul_f32_e32 v0, 0x4f7ffffe, v0
	v_cvt_u32_f32_e32 v2, v0
	s_waitcnt lgkmcnt(0)
	v_lshl_add_u64 v[0:1], s[18:19], 0, v[96:97]
	v_lshl_add_u64 v[98:99], v[0:1], 0, s[4:5]
	v_lshlrev_b32_e32 v0, 5, v208
	v_readfirstlane_b32 s8, v2
	s_mul_i32 s7, s7, s8
	s_mul_hi_u32 s7, s8, s7
	s_add_i32 s8, s8, s7
	s_lshr_b32 s7, s8, 18
	s_mul_i32 s7, s7, s6
	s_sub_i32 s7, 0x4000, s7
	s_sub_i32 s8, s7, s6
	s_cmp_ge_u32 s7, s6
	s_cselect_b32 s7, s8, s7
	s_sub_i32 s8, s7, s6
	s_cmp_ge_u32 s7, s6
	s_cselect_b32 s8, s8, s7
	s_cmpk_lt_i32 s24, 0x4000
	s_cselect_b64 s[6:7], -1, 0
	s_cmp_eq_u32 s8, 0
	s_load_dwordx4 s[12:15], s[0:1], 0x40
	s_load_dwordx2 s[8:9], s[0:1], 0x50
	v_mov_b32_e32 v1, v97
	s_mov_b64 s[4:5], 0x1000
	s_waitcnt lgkmcnt(0)
	v_lshl_add_u64 v[100:101], s[14:15], 0, v[0:1]
	v_lshl_add_u64 v[102:103], s[8:9], 0, v[0:1]
	v_cndmask_b32_e64 v0, 0, 1, s[6:7]
	v_lshl_add_u64 v[104:105], v[100:101], 0, s[4:5]
	v_cmp_ne_u32_e64 s[4:5], 1, v0
	s_cbranch_scc1 .LBB0_754
	s_and_b64 vcc, exec, s[4:5]
	s_cbranch_vccnz .LBB0_753
	v_mbcnt_lo_u32_b32 v0, -1, 0
	v_mbcnt_hi_u32_b32 v0, -1, v0
	v_and_b32_e32 v2, 64, v0
	v_xor_b32_e32 v1, 32, v0
	v_add_u32_e32 v2, 64, v2
	v_cmp_lt_i32_e32 vcc, v1, v2
	s_ashr_i32 s25, s24, 31
	s_lshl_b64 s[6:7], s[24:25], 11
	v_cndmask_b32_e32 v1, v0, v1, vcc
	v_lshlrev_b32_e32 v12, 2, v1
	v_xor_b32_e32 v1, 16, v0
	v_cmp_lt_i32_e32 vcc, v1, v2
	s_add_u32 s6, s18, s6
	v_mov_b32_e32 v97, 0
	v_cndmask_b32_e32 v1, v0, v1, vcc
	v_lshlrev_b32_e32 v13, 2, v1
	v_xor_b32_e32 v1, 8, v0
	v_cmp_lt_i32_e32 vcc, v1, v2
	s_addc_u32 s7, s19, s7
	s_ashr_i32 s99, s98, 31
	v_cndmask_b32_e32 v1, v0, v1, vcc
	v_lshlrev_b32_e32 v14, 2, v1
	v_xor_b32_e32 v1, 4, v0
	v_cmp_lt_i32_e32 vcc, v1, v2
	s_lshl_b64 s[8:9], s[24:25], 10
	v_mov_b32_e32 v18, 0x358637bd
	v_cndmask_b32_e32 v1, v0, v1, vcc
	v_lshlrev_b32_e32 v15, 2, v1
	v_xor_b32_e32 v1, 2, v0
	v_cmp_lt_i32_e32 vcc, v1, v2
	s_mov_b32 s10, 0x800000
	s_mov_b32 s11, s24
	v_cndmask_b32_e32 v1, v0, v1, vcc
	v_lshlrev_b32_e32 v16, 2, v1
	v_xor_b32_e32 v1, 1, v0
	v_cmp_lt_i32_e32 vcc, v1, v2
	s_nop 1
	v_cndmask_b32_e32 v0, v0, v1, vcc
	v_lshlrev_b32_e32 v17, 2, v0
	v_lshl_add_u64 v[0:1], s[6:7], 0, v[96:97]
	s_mov_b64 s[6:7], 0xe000400
	v_lshl_add_u64 v[8:9], v[0:1], 0, s[6:7]
	s_lshl_b64 s[6:7], s[98:99], 11
	s_add_u32 s8, s18, s8
	s_addc_u32 s9, s19, s9
	v_lshl_add_u64 v[0:1], s[8:9], 0, v[96:97]
	s_mov_b64 s[8:9], 0xa000000
	v_lshl_add_u64 v[10:11], v[0:1], 0, s[8:9]
	s_lshl_b64 s[8:9], s[98:99], 10
	s_branch .LBB0_748
; __device__ __forceinline__ unsigned pk2(float lo, float hi) { return pg8::cvt_pk_bf16(lo, hi); }
; template <int NR>
; __device__ __forceinline__ void conv_rows(const Args& a, int r0, int rstride, int lane) {
;     ...
;     for (int i = 0; i < NR; ++i) { const int row = r0 + i * rstride, t = row & (SEQ - 1);
;         bq[i] = *(const v4u*)(BCp + (size_t)row * 512 + c0); u0[i] = *(const v4u*)(CUp + (size_t)row * 512 + c0);
;         u1[i] = (v4u){0, 0, 0, 0}; u2[i] = (v4u){0, 0, 0, 0};
;         if (t >= 1) u1[i] = *(const v4u*)(CUp + (size_t)(row - 1) * 512 + c0);
;         if (t >= 2) u2[i] = *(const v4u*)(CUp + (size_t)(row - 2) * 512 + c0); }
;     const float* cw = a.in[I_CONVW] + c0; const float* gn = a.in[I_CONVN] + c0;
;     const f32x4 w0a = *(const f32x4*)(cw), w0b = *(const f32x4*)(cw + 4), w1a = *(const f32x4*)(cw + 512), w1b = *(const f32x4*)(cw + 516), w2a = *(const f32x4*)(cw + 1024), w2b = *(const f32x4*)(cw + 1028);
;     const f32x4 ga = *(const f32x4*)(gn), gb = *(const f32x4*)(gn + 4);
; #pragma unroll
;     for (int i = 0; i < NR; ++i) { const int row = r0 + i * rstride; float y[8]; float s = 0.f;
; #pragma unroll
;         for (int j = 0; j < 8; ++j) { const int sh = (j & 1) * 16; const unsigned ub = bq[i][j >> 1], x0 = u0[i][j >> 1], x1 = u1[i][j >> 1], x2 = u2[i][j >> 1];
;             const float B = __uint_as_float(((ub >> sh) & 0xffffu) << 16), c_0 = __uint_as_float(((x0 >> sh) & 0xffffu) << 16), c_1 = __uint_as_float(((x1 >> sh) & 0xffffu) << 16), c_2 = __uint_as_float(((x2 >> sh) & 0xffffu) << 16);
;             const float k0 = j < 4 ? w0a[j & 3] : w0b[j & 3], k1 = j < 4 ? w1a[j & 3] : w1b[j & 3], k2 = j < 4 ? w2a[j & 3] : w2b[j & 3];
;             y[j] = B * (k0 * c_2 + k1 * c_1 + k2 * c_0); s += y[j] * y[j]; }
;         s = wave_sum(s); const float rs = rsqrtf(s * (1.f / 512.f) + EPS);
;         v4u o; o.x = pk2(y[0] * rs * ga[0], y[1] * rs * ga[1]); o.y = pk2(y[2] * rs * ga[2], y[3] * rs * ga[3]); o.z = pk2(y[4] * rs * gb[0], y[5] * rs * gb[1]); o.w = pk2(y[6] * rs * gb[2], y[7] * rs * gb[3]);
;         pg8::st_wt16((bf16*)(ws + WS_MIX) + (size_t)row * 1024 + 512 + c0, o); }
.LBB0_747:
	global_load_dwordx4 v[20:23], v[10:11], off
	global_load_dwordx4 v[24:27], v[100:101], off offset:2064
	global_load_dwordx4 v[28:31], v[100:101], off offset:2048
	v_add_co_u32_e32 v60, vcc, 0x1000000, v10
	global_load_dwordx4 v[32:35], v[100:101], off
	global_load_dwordx4 v[36:39], v[100:101], off offset:16
	v_addc_co_u32_e32 v61, vcc, 0, v11, vcc
	global_load_dwordx4 v[40:43], v[60:61], off
	global_load_dwordx4 v[44:47], v[104:105], off offset:16
	global_load_dwordx4 v[48:51], v[104:105], off
	global_load_dwordx4 v[52:55], v[102:103], off offset:16
	global_load_dwordx4 v[56:59], v[102:103], off
	s_waitcnt vmcnt(10)
	v_lshlrev_b32_e32 v60, 16, v7
	v_and_b32_e32 v61, 0xffff0000, v7
	v_lshlrev_b32_e32 v62, 16, v3
	v_and_b32_e32 v63, 0xffff0000, v3
	v_lshlrev_b32_e32 v64, 16, v6
	v_and_b32_e32 v65, 0xffff0000, v6
	v_lshlrev_b32_e32 v6, 16, v2
	v_and_b32_e32 v7, 0xffff0000, v2
	v_lshlrev_b32_e32 v2, 16, v5
	v_and_b32_e32 v3, 0xffff0000, v5
	v_lshlrev_b32_e32 v66, 16, v1
	v_and_b32_e32 v67, 0xffff0000, v1
	v_lshlrev_b32_e32 v68, 16, v4
	v_and_b32_e32 v69, 0xffff0000, v4
	v_lshlrev_b32_e32 v4, 16, v0
	v_and_b32_e32 v5, 0xffff0000, v0
	s_add_i32 s11, s11, s98
	s_cmpk_lt_i32 s11, 0x4000
	v_lshl_add_u64 v[10:11], v[10:11], 0, s[8:9]
	s_waitcnt vmcnt(9)
	v_lshlrev_b32_e32 v0, 16, v23
	v_and_b32_e32 v1, 0xffff0000, v23
	s_waitcnt vmcnt(8)
	v_pk_mul_f32 v[6:7], v[24:25], v[6:7]
	v_lshlrev_b32_e32 v24, 16, v22
	v_and_b32_e32 v25, 0xffff0000, v22
	s_waitcnt vmcnt(7)
	v_pk_mul_f32 v[22:23], v[30:31], v[66:67]
	v_pk_mul_f32 v[4:5], v[28:29], v[4:5]
	s_waitcnt vmcnt(6)
	v_pk_fma_f32 v[2:3], v[34:35], v[2:3], v[22:23]
	v_pk_fma_f32 v[4:5], v[32:33], v[68:69], v[4:5]
	s_waitcnt vmcnt(4)
	v_lshlrev_b32_e32 v34, 16, v40
	v_and_b32_e32 v35, 0xffff0000, v40
	v_pk_mul_f32 v[26:27], v[26:27], v[62:63]
	v_lshlrev_b32_e32 v28, 16, v20
	v_and_b32_e32 v29, 0xffff0000, v20
	v_lshlrev_b32_e32 v32, 16, v41
	v_and_b32_e32 v33, 0xffff0000, v41
	s_waitcnt vmcnt(2)
	v_pk_fma_f32 v[4:5], v[48:49], v[34:35], v[4:5]
	v_lshlrev_b32_e32 v30, 16, v21
	v_and_b32_e32 v31, 0xffff0000, v21
	v_pk_fma_f32 v[20:21], v[38:39], v[60:61], v[26:27]
	v_pk_fma_f32 v[6:7], v[36:37], v[64:65], v[6:7]
	v_lshlrev_b32_e32 v26, 16, v42
	v_and_b32_e32 v27, 0xffff0000, v42
	v_pk_fma_f32 v[2:3], v[50:51], v[32:33], v[2:3]
	v_pk_mul_f32 v[4:5], v[4:5], v[28:29]
	v_pk_fma_f32 v[6:7], v[44:45], v[26:27], v[6:7]
	v_pk_mul_f32 v[2:3], v[2:3], v[30:31]
	v_pk_mul_f32 v[26:27], v[4:5], v[4:5]
	v_pk_mul_f32 v[6:7], v[6:7], v[24:25]
	v_pk_mul_f32 v[24:25], v[2:3], v[2:3]
	v_add_f32_e32 v19, v26, v27
	v_lshlrev_b32_e32 v22, 16, v43
	v_and_b32_e32 v23, 0xffff0000, v43
	v_add_f32_e32 v19, v24, v19
	v_pk_fma_f32 v[20:21], v[46:47], v[22:23], v[20:21]
	v_pk_mul_f32 v[22:23], v[6:7], v[6:7]
	v_add_f32_e32 v19, v25, v19
	v_pk_mul_f32 v[0:1], v[20:21], v[0:1]
	v_add_f32_e32 v19, v22, v19
	v_pk_mul_f32 v[20:21], v[0:1], v[0:1]
	v_add_f32_e32 v19, v23, v19
	v_add_f32_e32 v19, v20, v19
	v_add_f32_e32 v19, v21, v19
	ds_bpermute_b32 v20, v17, v19
	s_waitcnt lgkmcnt(0)
	v_add_f32_e32 v19, v19, v20
	ds_bpermute_b32 v20, v16, v19
	s_waitcnt lgkmcnt(0)
	v_add_f32_e32 v19, v19, v20
	ds_bpermute_b32 v20, v15, v19
	s_waitcnt lgkmcnt(0)
	v_add_f32_e32 v19, v19, v20
	ds_bpermute_b32 v20, v14, v19
	s_waitcnt lgkmcnt(0)
	v_add_f32_e32 v19, v19, v20
	ds_bpermute_b32 v20, v13, v19
	s_waitcnt lgkmcnt(0)
	v_add_f32_e32 v19, v19, v20
	ds_bpermute_b32 v20, v12, v19
	s_waitcnt lgkmcnt(0)
	v_add_f32_e32 v19, v19, v20
	v_fmamk_f32 v19, v19, 0x3b000000, v18
	v_mul_f32_e32 v20, 0x4b800000, v19
	v_cmp_gt_f32_e32 vcc, s10, v19
	s_nop 1
	v_cndmask_b32_e32 v19, v19, v20, vcc
	v_rsq_f32_e32 v19, v19
	s_nop 0
	v_mul_f32_e32 v20, 0x45800000, v19
	v_cndmask_b32_e32 v20, v19, v20, vcc
	v_pk_mul_f32 v[4:5], v[4:5], v[20:21] op_sel_hi:[1,0]
	v_pk_mul_f32 v[2:3], v[2:3], v[20:21] op_sel_hi:[1,0]
	v_pk_mul_f32 v[6:7], v[6:7], v[20:21] op_sel_hi:[1,0]
	v_pk_mul_f32 v[0:1], v[0:1], v[20:21] op_sel_hi:[1,0]
	s_waitcnt vmcnt(0)
	v_pk_mul_f32 v[4:5], v[56:57], v[4:5]
	v_pk_mul_f32 v[2:3], v[58:59], v[2:3]
	v_pk_mul_f32 v[6:7], v[52:53], v[6:7]
	v_pk_mul_f32 v[20:21], v[54:55], v[0:1]
	v_cvt_pk_bf16_f32 v0, v4, v5
	v_cvt_pk_bf16_f32 v1, v2, v3
	v_cvt_pk_bf16_f32 v2, v6, v7
	v_cvt_pk_bf16_f32 v3, v20, v21
	global_store_dwordx4 v[8:9], v[0:3], off
	v_lshl_add_u64 v[8:9], v[8:9], 0, s[6:7]
	s_cbranch_scc0 .LBB0_753

; template <int NR>
; __device__ __forceinline__ void conv_rows(const Args& a, int r0, int rstride, int lane) {
;     ...
;     for (int i = 0; i < NR; ++i) { const int row = r0 + i * rstride, t = row & (SEQ - 1);
;         bq[i] = *(const v4u*)(BCp + (size_t)row * 512 + c0); u0[i] = *(const v4u*)(CUp + (size_t)row * 512 + c0);
;         u1[i] = (v4u){0, 0, 0, 0}; u2[i] = (v4u){0, 0, 0, 0};
;         if (t >= 1) u1[i] = *(const v4u*)(CUp + (size_t)(row - 1) * 512 + c0);
;         if (t >= 2) u2[i] = *(const v4u*)(CUp + (size_t)(row - 2) * 512 + c0); }
;     const float* cw = a.in[I_CONVW] + c0; const float* gn = a.in[I_CONVN] + c0;
;     const f32x4 w0a = *(const f32x4*)(cw), w0b = *(const f32x4*)(cw + 4), w1a = *(const f32x4*)(cw + 512), w1b = *(const f32x4*)(cw + 516), w2a = *(const f32x4*)(cw + 1024), w2b = *(const f32x4*)(cw + 1028);
;     const f32x4 ga = *(const f32x4*)(gn), gb = *(const f32x4*)(gn + 4);
; #pragma unroll
;     for (int i = 0; i < NR; ++i) { const int row = r0 + i * rstride; float y[8]; float s = 0.f;
; #pragma unroll
;         for (int j = 0; j < 8; ++j) { const int sh = (j & 1) * 16; const unsigned ub = bq[i][j >> 1], x0 = u0[i][j >> 1], x1 = u1[i][j >> 1], x2 = u2[i][j >> 1];
;             const float B = __uint_as_float(((ub >> sh) & 0xffffu) << 16), c_0 = __uint_as_float(((x0 >> sh) & 0xffffu) << 16), c_1 = __uint_as_float(((x1 >> sh) & 0xffffu) << 16), c_2 = __uint_as_float(((x2 >> sh) & 0xffffu) << 16);
;             const float k0 = j < 4 ? w0a[j & 3] : w0b[j & 3], k1 = j < 4 ? w1a[j & 3] : w1b[j & 3], k2 = j < 4 ? w2a[j & 3] : w2b[j & 3];
;             y[j] = B * (k0 * c_2 + k1 * c_1 + k2 * c_0); s += y[j] * y[j]; }
;         s = wave_sum(s); const float rs = rsqrtf(s * (1.f / 512.f) + EPS);
.LBB0_754:
.LBB0_755:
	s_and_b64 vcc, exec, s[4:5]
	s_cbranch_vccnz .LBB0_939
	v_lshlrev_b32_e32 v0, 3, v208
	v_lshlrev_b32_e32 v106, 1, v0
	v_mov_b32_e32 v107, 0
	v_lshl_add_u64 v[0:1], s[18:19], 0, v[106:107]
	s_mov_b64 s[4:5], 0xa000000
	v_lshl_add_u64 v[108:109], v[0:1], 0, s[4:5]
	v_mbcnt_lo_u32_b32 v0, -1, 0
	v_mbcnt_hi_u32_b32 v0, -1, v0
	v_and_b32_e32 v1, 64, v0
	v_add_u32_e32 v1, 64, v1
	v_xor_b32_e32 v2, 1, v0
	v_cmp_lt_i32_e32 vcc, v2, v1
	s_lshl_b32 s7, s98, 1
	s_mul_i32 s9, s98, 3
	v_cndmask_b32_e32 v2, v0, v2, vcc
	v_lshlrev_b32_e32 v97, 2, v2
	v_xor_b32_e32 v2, 2, v0
	v_cmp_lt_i32_e32 vcc, v2, v1
	s_mov_b32 s6, 0x3b000000
	s_mov_b32 s8, 0x358637bd
	v_cndmask_b32_e32 v2, v0, v2, vcc
	v_lshlrev_b32_e32 v110, 2, v2
	v_xor_b32_e32 v2, 4, v0
	v_cmp_lt_i32_e32 vcc, v2, v1
	s_mov_b32 s22, 0x800000
	s_mov_b32 s23, 0xe000000
	v_cndmask_b32_e32 v2, v0, v2, vcc
	v_lshlrev_b32_e32 v111, 2, v2
	v_xor_b32_e32 v2, 8, v0
	v_cmp_lt_i32_e32 vcc, v2, v1
	s_nop 1
	v_cndmask_b32_e32 v2, v0, v2, vcc
	v_lshlrev_b32_e32 v112, 2, v2
	v_xor_b32_e32 v2, 16, v0
	v_cmp_lt_i32_e32 vcc, v2, v1
	s_nop 1
	v_cndmask_b32_e32 v2, v0, v2, vcc
	v_lshlrev_b32_e32 v113, 2, v2
	v_xor_b32_e32 v2, 32, v0
	v_cmp_lt_i32_e32 vcc, v2, v1
	s_nop 1
	v_cndmask_b32_e32 v0, v0, v2, vcc
	v_lshlrev_b32_e32 v114, 2, v0
	s_branch .LBB0_758
.LBB0_757:
	global_load_dwordx4 v[72:75], v[100:101], off offset:2064
	global_load_dwordx4 v[40:43], v[100:101], off offset:2048
	global_load_dwordx4 v[76:79], v[100:101], off offset:16
	global_load_dwordx4 v[44:47], v[100:101], off
	global_load_dwordx4 v[68:71], v[104:105], off offset:16
	global_load_dwordx4 v[36:39], v[104:105], off
	global_load_dwordx4 v[16:19], v[102:103], off offset:16
	global_load_dwordx4 v[20:23], v[102:103], off
	v_lshlrev_b32_e32 v120, 16, v3
	v_and_b32_e32 v121, 0xffff0000, v3
	v_lshlrev_b32_e32 v116, 16, v87
	v_and_b32_e32 v117, 0xffff0000, v87
	v_lshlrev_b32_e32 v118, 16, v83
	v_and_b32_e32 v119, 0xffff0000, v83
	v_lshlrev_b32_e32 v122, 16, v91
	v_and_b32_e32 v123, 0xffff0000, v91
	v_lshlrev_b32_e32 v124, 16, v86
	v_and_b32_e32 v125, 0xffff0000, v86
	v_lshlrev_b32_e32 v86, 16, v82
	v_and_b32_e32 v87, 0xffff0000, v82
	v_lshlrev_b32_e32 v82, 16, v2
	v_and_b32_e32 v83, 0xffff0000, v2
	v_lshlrev_b32_e32 v2, 16, v90
	v_and_b32_e32 v3, 0xffff0000, v90
	v_lshlrev_b32_e32 v90, 16, v85
	v_and_b32_e32 v91, 0xffff0000, v85
	v_lshlrev_b32_e32 v126, 16, v81
	v_and_b32_e32 v127, 0xffff0000, v81
	v_lshlrev_b32_e32 v128, 16, v1
	v_and_b32_e32 v129, 0xffff0000, v1
	v_lshlrev_b32_e32 v130, 16, v89
	v_and_b32_e32 v131, 0xffff0000, v89
	v_lshlrev_b32_e32 v132, 16, v84
	v_and_b32_e32 v133, 0xffff0000, v84
	v_lshlrev_b32_e32 v84, 16, v80
	v_and_b32_e32 v85, 0xffff0000, v80
	v_lshlrev_b32_e32 v80, 16, v0
	v_and_b32_e32 v81, 0xffff0000, v0
	v_lshlrev_b32_e32 v0, 16, v88
	v_and_b32_e32 v1, 0xffff0000, v88
	s_waitcnt vmcnt(13)
	v_lshlrev_b32_e32 v88, 16, v67
	v_and_b32_e32 v89, 0xffff0000, v67
	s_waitcnt vmcnt(12)
	v_lshlrev_b32_e32 v134, 16, v63
	v_and_b32_e32 v135, 0xffff0000, v63
	v_lshlrev_b32_e32 v140, 16, v66
	v_and_b32_e32 v141, 0xffff0000, v66
	v_lshlrev_b32_e32 v66, 16, v62
	v_and_b32_e32 v67, 0xffff0000, v62
	v_lshlrev_b32_e32 v62, 16, v6
	v_and_b32_e32 v63, 0xffff0000, v6
	v_lshlrev_b32_e32 v136, 16, v7
	v_and_b32_e32 v137, 0xffff0000, v7
	v_lshlrev_b32_e32 v6, 16, v94
	v_and_b32_e32 v7, 0xffff0000, v94
	v_lshlrev_b32_e32 v138, 16, v95
	v_and_b32_e32 v139, 0xffff0000, v95
	v_lshlrev_b32_e32 v94, 16, v65
	v_and_b32_e32 v95, 0xffff0000, v65
	v_and_b32_e32 v65, 0xffff0000, v60
	s_add_i32 s26, s10, s98
	s_add_i32 s26, s26, s98
	s_lshl_b64 s[4:5], s[24:25], 11
	s_add_u32 s4, s18, s4
	s_addc_u32 s5, s19, s5
	s_waitcnt vmcnt(7)
	v_pk_mul_f32 v[120:121], v[74:75], v[120:121]
	s_waitcnt vmcnt(6)
	v_pk_mul_f32 v[80:81], v[40:41], v[80:81]
	v_pk_mul_f32 v[62:63], v[72:73], v[62:63]
	s_waitcnt vmcnt(5)
	v_pk_fma_f32 v[120:121], v[78:79], v[122:123], v[120:121]
	s_waitcnt vmcnt(4)
	v_pk_fma_f32 v[0:1], v[44:45], v[0:1], v[80:81]
	v_pk_fma_f32 v[6:7], v[76:77], v[6:7], v[62:63]
	s_waitcnt vmcnt(3)
	v_pk_fma_f32 v[62:63], v[70:71], v[118:119], v[120:121]
	s_waitcnt vmcnt(2)
	v_pk_fma_f32 v[0:1], v[36:37], v[84:85], v[0:1]
	v_pk_mul_f32 v[84:85], v[62:63], v[116:117]
	v_lshlrev_b32_e32 v116, 16, v5
	v_and_b32_e32 v117, 0xffff0000, v5
	v_pk_fma_f32 v[66:67], v[68:69], v[66:67], v[6:7]
	v_lshlrev_b32_e32 v118, 16, v93
	v_and_b32_e32 v119, 0xffff0000, v93
	v_pk_mul_f32 v[116:117], v[42:43], v[116:117]
	v_pk_mul_f32 v[62:63], v[66:67], v[140:141]
	v_lshlrev_b32_e32 v66, 16, v61
	v_and_b32_e32 v67, 0xffff0000, v61
	v_pk_fma_f32 v[116:117], v[46:47], v[118:119], v[116:117]
	v_and_b32_e32 v61, 0xffff0000, v4
	v_pk_fma_f32 v[66:67], v[38:39], v[66:67], v[116:117]
	v_and_b32_e32 v5, 0xffff0000, v92
	v_pk_mul_f32 v[66:67], v[66:67], v[94:95]
	v_lshlrev_b32_e32 v94, 16, v64
	v_and_b32_e32 v95, 0xffff0000, v64
	v_lshlrev_b32_e32 v64, 16, v60
	v_lshlrev_b32_e32 v60, 16, v4
	v_lshlrev_b32_e32 v4, 16, v92
	v_pk_mul_f32 v[60:61], v[40:41], v[60:61]
	v_pk_mul_f32 v[82:83], v[72:73], v[82:83]
	v_pk_fma_f32 v[4:5], v[44:45], v[4:5], v[60:61]
	v_pk_mul_f32 v[128:129], v[42:43], v[128:129]
	v_pk_fma_f32 v[4:5], v[36:37], v[64:65], v[4:5]
	v_pk_fma_f32 v[2:3], v[76:77], v[2:3], v[82:83]
	v_pk_fma_f32 v[82:83], v[46:47], v[130:131], v[128:129]
	v_pk_mul_f32 v[0:1], v[0:1], v[132:133]
	v_pk_mul_f32 v[4:5], v[4:5], v[94:95]
	v_pk_fma_f32 v[82:83], v[38:39], v[126:127], v[82:83]
	v_mov_b32_e32 v94, v5
	v_mov_b32_e32 v95, v1
	v_pk_mul_f32 v[136:137], v[74:75], v[136:137]
	v_pk_fma_f32 v[2:3], v[68:69], v[86:87], v[2:3]
	v_pk_mul_f32 v[82:83], v[82:83], v[90:91]
	v_mov_b32_e32 v92, v4
	v_mov_b32_e32 v93, v0
	v_pk_mul_f32 v[94:95], v[94:95], v[94:95]
	v_pk_fma_f32 v[80:81], v[78:79], v[138:139], v[136:137]
	v_pk_mul_f32 v[2:3], v[2:3], v[124:125]
	v_mov_b32_e32 v60, v66
	v_mov_b32_e32 v61, v82
	v_pk_fma_f32 v[92:93], v[92:93], v[92:93], v[94:95]
	v_pk_fma_f32 v[80:81], v[70:71], v[134:135], v[80:81]
	v_pk_mul_f32 v[86:87], v[2:3], v[2:3]
	v_pk_mul_f32 v[90:91], v[62:63], v[62:63]
	v_mov_b32_e32 v64, v67
	v_mov_b32_e32 v65, v83
	v_pk_fma_f32 v[60:61], v[60:61], v[60:61], v[92:93]
	v_pk_mul_f32 v[6:7], v[80:81], v[88:89]
	v_pk_fma_f32 v[60:61], v[64:65], v[64:65], v[60:61]
	v_mov_b32_e32 v64, v90
	v_mov_b32_e32 v65, v86
	v_pk_mul_f32 v[80:81], v[84:85], v[84:85]
	v_pk_mul_f32 v[88:89], v[6:7], v[6:7]
	v_pk_add_f32 v[60:61], v[64:65], v[60:61]
	v_mov_b32_e32 v86, v91
	v_pk_add_f32 v[60:61], v[86:87], v[60:61]
	v_mov_b32_e32 v64, v88
	v_mov_b32_e32 v65, v80
	v_pk_add_f32 v[60:61], v[64:65], v[60:61]
	v_mov_b32_e32 v80, v89
	v_pk_add_f32 v[60:61], v[80:81], v[60:61]
	ds_bpermute_b32 v65, v97, v61
	ds_bpermute_b32 v64, v97, v60
	s_waitcnt lgkmcnt(0)
; __device__ __forceinline__ unsigned pk2(float lo, float hi) { return pg8::cvt_pk_bf16(lo, hi); }
; template <int NR>
; __device__ __forceinline__ void conv_rows(const Args& a, int r0, int rstride, int lane) {
;     ...
;     for (int i = 0; i < NR; ++i) { const int row = r0 + i * rstride; float y[8]; float s = 0.f;
; #pragma unroll
;         for (int j = 0; j < 8; ++j) { const int sh = (j & 1) * 16; const unsigned ub = bq[i][j >> 1], x0 = u0[i][j >> 1], x1 = u1[i][j >> 1], x2 = u2[i][j >> 1];
;             const float B = __uint_as_float(((ub >> sh) & 0xffffu) << 16), c_0 = __uint_as_float(((x0 >> sh) & 0xffffu) << 16), c_1 = __uint_as_float(((x1 >> sh) & 0xffffu) << 16), c_2 = __uint_as_float(((x2 >> sh) & 0xffffu) << 16);
;             const float k0 = j < 4 ? w0a[j & 3] : w0b[j & 3], k1 = j < 4 ? w1a[j & 3] : w1b[j & 3], k2 = j < 4 ? w2a[j & 3] : w2b[j & 3];
;             y[j] = B * (k0 * c_2 + k1 * c_1 + k2 * c_0); s += y[j] * y[j]; }
;         s = wave_sum(s); const float rs = rsqrtf(s * (1.f / 512.f) + EPS);
;         v4u o; o.x = pk2(y[0] * rs * ga[0], y[1] * rs * ga[1]); o.y = pk2(y[2] * rs * ga[2], y[3] * rs * ga[3]); o.z = pk2(y[4] * rs * gb[0], y[5] * rs * gb[1]); o.w = pk2(y[6] * rs * gb[2], y[7] * rs * gb[3]);
;         pg8::st_wt16((bf16*)(ws + WS_MIX) + (size_t)row * 1024 + 512 + c0, o); }
	v_pk_add_f32 v[60:61], v[60:61], v[64:65]
	ds_bpermute_b32 v65, v110, v61
	ds_bpermute_b32 v64, v110, v60
	s_waitcnt lgkmcnt(0)
	v_pk_add_f32 v[60:61], v[60:61], v[64:65]
	ds_bpermute_b32 v65, v111, v61
	ds_bpermute_b32 v64, v111, v60
	s_waitcnt lgkmcnt(0)
	v_pk_add_f32 v[60:61], v[60:61], v[64:65]
	ds_bpermute_b32 v65, v112, v61
	ds_bpermute_b32 v64, v112, v60
	s_waitcnt lgkmcnt(0)
	v_pk_add_f32 v[60:61], v[60:61], v[64:65]
	ds_bpermute_b32 v65, v113, v61
	ds_bpermute_b32 v64, v113, v60
	s_waitcnt lgkmcnt(0)
	v_pk_add_f32 v[60:61], v[60:61], v[64:65]
	ds_bpermute_b32 v65, v114, v61
	ds_bpermute_b32 v64, v114, v60
	s_waitcnt lgkmcnt(0)
	v_pk_add_f32 v[64:65], v[60:61], v[64:65]
	v_mov_b64_e32 v[60:61], s[8:9]
	v_pk_fma_f32 v[80:81], v[64:65], s[6:7], v[60:61] op_sel_hi:[1,0,0]
	s_nop 0
	v_mul_f32_e32 v64, 0x4b800000, v81
	v_cmp_gt_f32_e32 vcc, s22, v81
	s_nop 1
	v_cndmask_b32_e32 v64, v81, v64, vcc
	v_rsq_f32_e32 v81, v64
	v_lshl_add_u64 v[64:65], s[4:5], 0, v[106:107]
	v_mul_f32_e32 v86, 0x45800000, v81
	v_cndmask_b32_e32 v86, v81, v86, vcc
	v_pk_mul_f32 v[0:1], v[0:1], v[86:87] op_sel_hi:[1,0]
	v_pk_mul_f32 v[82:83], v[82:83], v[86:87] op_sel_hi:[1,0]
	s_waitcnt vmcnt(0)
	v_pk_mul_f32 v[0:1], v[20:21], v[0:1]
	v_pk_mul_f32 v[82:83], v[22:23], v[82:83]
	v_cvt_pk_bf16_f32 v0, v0, v1
	v_cvt_pk_bf16_f32 v1, v82, v83
	v_pk_mul_f32 v[2:3], v[2:3], v[86:87] op_sel_hi:[1,0]
	v_pk_mul_f32 v[82:83], v[84:85], v[86:87] op_sel_hi:[1,0]
	v_lshlrev_b32_e32 v84, 16, v11
	v_and_b32_e32 v85, 0xffff0000, v11
	v_pk_mul_f32 v[2:3], v[16:17], v[2:3]
	v_pk_mul_f32 v[82:83], v[18:19], v[82:83]
	v_mul_f32_e32 v81, 0x4b800000, v80
	v_cmp_gt_f32_e32 vcc, s22, v80
	v_lshlrev_b32_e32 v86, 16, v59
	v_and_b32_e32 v87, 0xffff0000, v59
	v_pk_mul_f32 v[84:85], v[74:75], v[84:85]
	v_cvt_pk_bf16_f32 v2, v2, v3
	v_cvt_pk_bf16_f32 v3, v82, v83
	v_cndmask_b32_e32 v80, v80, v81, vcc
	v_lshlrev_b32_e32 v82, 16, v51
	v_and_b32_e32 v83, 0xffff0000, v51
	v_pk_fma_f32 v[84:85], v[78:79], v[86:87], v[84:85]
	v_rsq_f32_e32 v88, v80
	v_lshlrev_b32_e32 v80, 16, v55
	v_and_b32_e32 v81, 0xffff0000, v55
	v_pk_fma_f32 v[82:83], v[70:71], v[82:83], v[84:85]
	v_lshlrev_b32_e32 v84, 16, v54
	v_and_b32_e32 v85, 0xffff0000, v54
	v_lshlrev_b32_e32 v54, 16, v50
	v_and_b32_e32 v55, 0xffff0000, v50
	v_lshlrev_b32_e32 v50, 16, v10
	v_and_b32_e32 v51, 0xffff0000, v10
	v_lshlrev_b32_e32 v10, 16, v58
	v_and_b32_e32 v11, 0xffff0000, v58
	v_pk_mul_f32 v[50:51], v[72:73], v[50:51]
	v_lshlrev_b32_e32 v86, 16, v57
	v_pk_fma_f32 v[10:11], v[76:77], v[10:11], v[50:51]
	v_and_b32_e32 v87, 0xffff0000, v57
	v_pk_fma_f32 v[10:11], v[68:69], v[54:55], v[10:11]
	v_lshlrev_b32_e32 v58, 16, v49
	v_pk_mul_f32 v[10:11], v[10:11], v[84:85]
	v_lshlrev_b32_e32 v84, 16, v9
	v_and_b32_e32 v85, 0xffff0000, v9
	v_pk_mul_f32 v[84:85], v[42:43], v[84:85]
	v_and_b32_e32 v59, 0xffff0000, v49
	v_pk_fma_f32 v[84:85], v[46:47], v[86:87], v[84:85]
	v_lshlrev_b32_e32 v54, 16, v53
	v_and_b32_e32 v55, 0xffff0000, v53
	v_pk_fma_f32 v[58:59], v[38:39], v[58:59], v[84:85]
	v_and_b32_e32 v53, 0xffff0000, v48
	v_pk_mul_f32 v[54:55], v[58:59], v[54:55]
	v_lshlrev_b32_e32 v58, 16, v52
	v_and_b32_e32 v59, 0xffff0000, v52
	v_lshlrev_b32_e32 v52, 16, v48
	v_lshlrev_b32_e32 v48, 16, v8
	v_and_b32_e32 v49, 0xffff0000, v8
	v_lshlrev_b32_e32 v8, 16, v56
	v_and_b32_e32 v9, 0xffff0000, v56
	v_pk_mul_f32 v[48:49], v[40:41], v[48:49]
	v_lshlrev_b32_e32 v56, 16, v31
	v_pk_fma_f32 v[8:9], v[44:45], v[8:9], v[48:49]
	v_lshlrev_b32_e32 v48, 16, v35
	v_pk_fma_f32 v[8:9], v[36:37], v[52:53], v[8:9]
	v_lshlrev_b32_e32 v52, 16, v15
	v_and_b32_e32 v53, 0xffff0000, v15
	v_and_b32_e32 v49, 0xffff0000, v35
	v_pk_mul_f32 v[52:53], v[74:75], v[52:53]
	v_and_b32_e32 v57, 0xffff0000, v31
	v_pk_fma_f32 v[48:49], v[78:79], v[48:49], v[52:53]
	v_and_b32_e32 v35, 0xffff0000, v14
	v_pk_fma_f32 v[48:49], v[70:71], v[56:57], v[48:49]
	v_lshlrev_b32_e32 v56, 16, v34
	v_and_b32_e32 v57, 0xffff0000, v34
	v_lshlrev_b32_e32 v34, 16, v14
	v_pk_mul_f32 v[14:15], v[72:73], v[34:35]
	v_lshlrev_b32_e32 v34, 16, v30
	v_pk_fma_f32 v[14:15], v[76:77], v[56:57], v[14:15]
	v_and_b32_e32 v35, 0xffff0000, v30
	v_pk_fma_f32 v[14:15], v[68:69], v[34:35], v[14:15]
	v_lshlrev_b32_e32 v30, 16, v26
	v_and_b32_e32 v31, 0xffff0000, v26
	v_lshlrev_b32_e32 v34, 16, v13
	v_and_b32_e32 v35, 0xffff0000, v13
	v_pk_mul_f32 v[14:15], v[14:15], v[30:31]
	v_lshlrev_b32_e32 v30, 16, v33
	v_and_b32_e32 v31, 0xffff0000, v33
	v_pk_mul_f32 v[34:35], v[42:43], v[34:35]
	v_and_b32_e32 v33, 0xffff0000, v12
	v_pk_fma_f32 v[30:31], v[46:47], v[30:31], v[34:35]
	v_lshlrev_b32_e32 v34, 16, v29
	v_and_b32_e32 v35, 0xffff0000, v29
	v_pk_fma_f32 v[30:31], v[38:39], v[34:35], v[30:31]
	v_lshlrev_b32_e32 v34, 16, v25
	v_and_b32_e32 v35, 0xffff0000, v25
	v_pk_mul_f32 v[30:31], v[30:31], v[34:35]
	v_lshlrev_b32_e32 v34, 16, v32
	v_and_b32_e32 v35, 0xffff0000, v32
	v_lshlrev_b32_e32 v32, 16, v12
	v_pk_mul_f32 v[12:13], v[40:41], v[32:33]
	v_lshlrev_b32_e32 v32, 16, v28
	v_pk_fma_f32 v[12:13], v[44:45], v[34:35], v[12:13]
	v_and_b32_e32 v33, 0xffff0000, v28
	v_pk_fma_f32 v[12:13], v[36:37], v[32:33], v[12:13]
	v_lshlrev_b32_e32 v28, 16, v24
	v_and_b32_e32 v29, 0xffff0000, v24
	v_pk_mul_f32 v[8:9], v[8:9], v[58:59]
	v_pk_mul_f32 v[12:13], v[12:13], v[28:29]
	v_mov_b32_e32 v35, v9
	v_mov_b32_e32 v34, v13
	v_mov_b32_e32 v32, v12
	v_mov_b32_e32 v33, v8
	v_pk_mul_f32 v[34:35], v[34:35], v[34:35]
	v_mov_b32_e32 v24, v30
	v_mov_b32_e32 v25, v54
	v_pk_fma_f32 v[32:33], v[32:33], v[32:33], v[34:35]
	v_pk_mul_f32 v[50:51], v[10:11], v[10:11]
	v_lshlrev_b32_e32 v58, 16, v27
	v_and_b32_e32 v59, 0xffff0000, v27
	v_pk_mul_f32 v[26:27], v[14:15], v[14:15]
	v_mov_b32_e32 v28, v31
	v_mov_b32_e32 v29, v55
	v_pk_fma_f32 v[24:25], v[24:25], v[24:25], v[32:33]
	v_pk_mul_f32 v[80:81], v[82:83], v[80:81]
	v_pk_mul_f32 v[48:49], v[48:49], v[58:59]
	v_pk_fma_f32 v[24:25], v[28:29], v[28:29], v[24:25]
	v_mov_b32_e32 v28, v26
	v_mov_b32_e32 v29, v50
	v_pk_mul_f32 v[82:83], v[80:81], v[80:81]
	v_pk_mul_f32 v[52:53], v[48:49], v[48:49]
	v_pk_add_f32 v[24:25], v[28:29], v[24:25]
	v_mov_b32_e32 v50, v27
	v_pk_add_f32 v[24:25], v[50:51], v[24:25]
	v_mov_b32_e32 v26, v52
	v_mov_b32_e32 v27, v82
	v_pk_add_f32 v[24:25], v[26:27], v[24:25]
	v_mov_b32_e32 v82, v53
	v_pk_add_f32 v[24:25], v[82:83], v[24:25]
	ds_bpermute_b32 v27, v97, v25
	ds_bpermute_b32 v26, v97, v24
	v_add_co_u32_e64 v28, s[4:5], s23, v64
	s_nop 1
	v_addc_co_u32_e64 v29, s[4:5], 0, v65, s[4:5]
	global_store_dwordx4 v[28:29], v[0:3], off offset:1024
	s_lshl_b64 s[4:5], s[10:11], 11
	s_add_u32 s4, s18, s4
	s_waitcnt lgkmcnt(0)
; __device__ __forceinline__ unsigned pk2(float lo, float hi) { return pg8::cvt_pk_bf16(lo, hi); }
; template <int NR>
; __device__ __forceinline__ void conv_rows(const Args& a, int r0, int rstride, int lane) {
;     ...
;     for (int i = 0; i < NR; ++i) { const int row = r0 + i * rstride; float y[8]; float s = 0.f;
; #pragma unroll
;         for (int j = 0; j < 8; ++j) { const int sh = (j & 1) * 16; const unsigned ub = bq[i][j >> 1], x0 = u0[i][j >> 1], x1 = u1[i][j >> 1], x2 = u2[i][j >> 1];
;             const float B = __uint_as_float(((ub >> sh) & 0xffffu) << 16), c_0 = __uint_as_float(((x0 >> sh) & 0xffffu) << 16), c_1 = __uint_as_float(((x1 >> sh) & 0xffffu) << 16), c_2 = __uint_as_float(((x2 >> sh) & 0xffffu) << 16);
;             const float k0 = j < 4 ? w0a[j & 3] : w0b[j & 3], k1 = j < 4 ? w1a[j & 3] : w1b[j & 3], k2 = j < 4 ? w2a[j & 3] : w2b[j & 3];
;             y[j] = B * (k0 * c_2 + k1 * c_1 + k2 * c_0); s += y[j] * y[j]; }
;         s = wave_sum(s); const float rs = rsqrtf(s * (1.f / 512.f) + EPS);
;         v4u o; o.x = pk2(y[0] * rs * ga[0], y[1] * rs * ga[1]); o.y = pk2(y[2] * rs * ga[2], y[3] * rs * ga[3]); o.z = pk2(y[4] * rs * gb[0], y[5] * rs * gb[1]); o.w = pk2(y[6] * rs * gb[2], y[7] * rs * gb[3]);
;         pg8::st_wt16((bf16*)(ws + WS_MIX) + (size_t)row * 1024 + 512 + c0, o); }
; __global__ void __launch_bounds__(NT, 2) hymba_fwd(Args args) {
;     ...
;         if (M % (4 * NGW) == 0) { for (int r = gw; r < M; r += 4 * NGW) conv_rows<4>(args, r, NGW, lane); } else { for (int r = gw; r < M; r += NGW) conv_rows<1>(args, r, NGW, lane); }
	v_pk_add_f32 v[2:3], v[24:25], v[26:27]
	ds_bpermute_b32 v25, v110, v3
	ds_bpermute_b32 v24, v110, v2
	v_mul_f32_e32 v0, 0x45800000, v88
	v_cndmask_b32_e32 v28, v88, v0, vcc
	v_pk_mul_f32 v[0:1], v[4:5], v[28:29] op_sel_hi:[1,0]
	v_pk_mul_f32 v[4:5], v[66:67], v[28:29] op_sel_hi:[1,0]
	s_waitcnt lgkmcnt(0)
	v_pk_add_f32 v[2:3], v[2:3], v[24:25]
	ds_bpermute_b32 v25, v111, v3
	ds_bpermute_b32 v24, v111, v2
	v_pk_mul_f32 v[0:1], v[20:21], v[0:1]
	v_pk_mul_f32 v[4:5], v[22:23], v[4:5]
	v_cvt_pk_bf16_f32 v0, v0, v1
	v_cvt_pk_bf16_f32 v1, v4, v5
	s_waitcnt lgkmcnt(0)
	v_pk_add_f32 v[24:25], v[2:3], v[24:25]
	ds_bpermute_b32 v27, v112, v25
	ds_bpermute_b32 v26, v112, v24
	v_pk_mul_f32 v[4:5], v[62:63], v[28:29] op_sel_hi:[1,0]
	s_addc_u32 s5, s19, s5
	v_pk_mul_f32 v[4:5], v[16:17], v[4:5]
	s_nop 0
	v_cvt_pk_bf16_f32 v2, v4, v5
	v_pk_mul_f32 v[4:5], v[6:7], v[28:29] op_sel_hi:[1,0]
	s_nop 0
	v_pk_mul_f32 v[4:5], v[18:19], v[4:5]
	s_nop 0
	v_cvt_pk_bf16_f32 v3, v4, v5
	s_waitcnt lgkmcnt(0)
	v_pk_add_f32 v[4:5], v[24:25], v[26:27]
	ds_bpermute_b32 v7, v113, v5
	ds_bpermute_b32 v6, v113, v4
	v_lshl_add_u64 v[24:25], s[4:5], 0, v[106:107]
	v_add_co_u32_e32 v24, vcc, s23, v24
	s_lshl_b64 s[4:5], s[14:15], 11
	s_waitcnt lgkmcnt(0)
	v_pk_add_f32 v[4:5], v[4:5], v[6:7]
	ds_bpermute_b32 v7, v114, v5
	ds_bpermute_b32 v6, v114, v4
	v_addc_co_u32_e32 v25, vcc, 0, v25, vcc
	global_store_dwordx4 v[24:25], v[0:3], off offset:1024
	s_add_u32 s4, s18, s4
	s_addc_u32 s5, s19, s5
	s_waitcnt lgkmcnt(0)
	v_pk_add_f32 v[0:1], v[4:5], v[6:7]
	v_lshl_add_u64 v[6:7], s[4:5], 0, v[106:107]
	v_pk_fma_f32 v[4:5], v[0:1], s[6:7], v[60:61] op_sel_hi:[1,0,0]
	s_nop 0
	v_mul_f32_e32 v0, 0x4b800000, v5
	v_cmp_gt_f32_e32 vcc, s22, v5
	s_nop 1
	v_cndmask_b32_e32 v0, v5, v0, vcc
	v_rsq_f32_e32 v0, v0
	v_mul_f32_e32 v5, 0x4b800000, v4
	v_mul_f32_e32 v1, 0x45800000, v0
	v_cndmask_b32_e32 v24, v0, v1, vcc
	v_pk_mul_f32 v[0:1], v[8:9], v[24:25] op_sel_hi:[1,0]
	v_pk_mul_f32 v[2:3], v[54:55], v[24:25] op_sel_hi:[1,0]
	v_pk_mul_f32 v[0:1], v[20:21], v[0:1]
	v_pk_mul_f32 v[2:3], v[22:23], v[2:3]
	v_cvt_pk_bf16_f32 v0, v0, v1
	v_cvt_pk_bf16_f32 v1, v2, v3
	v_pk_mul_f32 v[2:3], v[10:11], v[24:25] op_sel_hi:[1,0]
	v_pk_mul_f32 v[8:9], v[80:81], v[24:25] op_sel_hi:[1,0]
	v_cmp_gt_f32_e32 vcc, s22, v4
	v_pk_mul_f32 v[2:3], v[16:17], v[2:3]
	v_pk_mul_f32 v[8:9], v[18:19], v[8:9]
	v_cndmask_b32_e32 v4, v4, v5, vcc
	v_cvt_pk_bf16_f32 v2, v2, v3
	v_cvt_pk_bf16_f32 v3, v8, v9
	v_rsq_f32_e32 v8, v4
	v_add_co_u32_e64 v4, s[4:5], s23, v6
	s_nop 1
	v_addc_co_u32_e64 v5, s[4:5], 0, v7, s[4:5]
	global_store_dwordx4 v[4:5], v[0:3], off offset:1024
	s_lshl_b64 s[4:5], s[20:21], 11
	s_add_u32 s4, s18, s4
	v_mul_f32_e32 v0, 0x45800000, v8
	v_cndmask_b32_e32 v4, v8, v0, vcc
	v_pk_mul_f32 v[0:1], v[12:13], v[4:5] op_sel_hi:[1,0]
	v_pk_mul_f32 v[2:3], v[30:31], v[4:5] op_sel_hi:[1,0]
	v_pk_mul_f32 v[0:1], v[20:21], v[0:1]
	v_pk_mul_f32 v[2:3], v[22:23], v[2:3]
	v_cvt_pk_bf16_f32 v0, v0, v1
	v_cvt_pk_bf16_f32 v1, v2, v3
	v_pk_mul_f32 v[2:3], v[14:15], v[4:5] op_sel_hi:[1,0]
	v_pk_mul_f32 v[4:5], v[48:49], v[4:5] op_sel_hi:[1,0]
	v_pk_mul_f32 v[2:3], v[16:17], v[2:3]
	v_pk_mul_f32 v[4:5], v[18:19], v[4:5]
	s_addc_u32 s5, s19, s5
	v_cvt_pk_bf16_f32 v2, v2, v3
	v_cvt_pk_bf16_f32 v3, v4, v5
	v_lshl_add_u64 v[4:5], s[4:5], 0, v[106:107]
	v_add_co_u32_e32 v4, vcc, 0xe000000, v4
	s_add_i32 s24, s26, s98
	s_nop 0
	v_addc_co_u32_e32 v5, vcc, 0, v5, vcc
	s_cmpk_gt_i32 s24, 0x3fff
	global_store_dwordx4 v[4:5], v[0:3], off offset:1024
	s_cbranch_scc1 .LBB0_939

; template <int NR>
; __device__ __forceinline__ void conv_rows(const Args& a, int r0, int rstride, int lane) {
;     ...
;     for (int i = 0; i < NR; ++i) { const int row = r0 + i * rstride, t = row & (SEQ - 1);
;         bq[i] = *(const v4u*)(BCp + (size_t)row * 512 + c0); u0[i] = *(const v4u*)(CUp + (size_t)row * 512 + c0);
;         u1[i] = (v4u){0, 0, 0, 0}; u2[i] = (v4u){0, 0, 0, 0};
;         if (t >= 1) u1[i] = *(const v4u*)(CUp + (size_t)(row - 1) * 512 + c0);
;         if (t >= 2) u2[i] = *(const v4u*)(CUp + (size_t)(row - 2) * 512 + c0); }
.LBB0_763:
	s_add_i32 s10, s24, s98
	s_ashr_i32 s11, s10, 31
	s_lshl_b64 s[4:5], s[10:11], 10
	v_lshl_add_u64 v[0:1], v[108:109], 0, s[4:5]
	v_lshl_add_u64 v[2:3], v[98:99], 0, s[4:5]
	global_load_dwordx4 v[64:67], v[0:1], off
	global_load_dwordx4 v[60:63], v[2:3], off
	s_and_b32 s4, s10, 0xfff
	s_cmp_eq_u32 s4, 0
	s_cbranch_scc1 .LBB0_765
	s_add_i32 s14, s10, -1
	s_ashr_i32 s15, s14, 31
	s_lshl_b64 s[14:15], s[14:15], 10
	v_lshl_add_u64 v[0:1], v[98:99], 0, s[14:15]
	global_load_dwordx4 v[20:23], v[0:1], off
	v_mov_b32_e32 v24, v107
	v_mov_b32_e32 v25, v107
	v_mov_b32_e32 v26, v107
	v_mov_b32_e32 v27, v107
	s_waitcnt vmcnt(0)
	v_mov_b64_e32 v[46:47], v[30:31]
	v_mov_b32_e32 v0, v16
	v_mov_b32_e32 v1, v17
	v_mov_b32_e32 v2, v18
	v_mov_b32_e32 v3, v19
	v_mov_b32_e32 v8, v107
	v_mov_b32_e32 v9, v107
	v_mov_b32_e32 v10, v107
	v_mov_b32_e32 v11, v107
	v_mov_b32_e32 v12, v107
	v_mov_b32_e32 v13, v107
	v_mov_b32_e32 v14, v107
	v_mov_b32_e32 v15, v107
	v_mov_b64_e32 v[42:43], v[26:27]
	v_mov_b64_e32 v[40:41], v[24:25]
	v_mov_b64_e32 v[34:35], v[18:19]
	v_mov_b64_e32 v[32:33], v[16:17]
	v_mov_b64_e32 v[44:45], v[28:29]
	v_mov_b32_e32 v4, v20
	v_mov_b32_e32 v5, v21
	v_mov_b32_e32 v6, v22
	v_mov_b32_e32 v7, v23
	v_mov_b64_e32 v[38:39], v[22:23]
	v_mov_b64_e32 v[36:37], v[20:21]
	s_branch .LBB0_766
